# sgu staging: the four unrolled iterations' input loads issued together at the top of each trip (one wait instead of four round trips); first four hops of each wave all-reduce done with DPP adds
# speedup vs baseline: 1.0081x; 1.0081x over previous
.LBB0_287:
	global_load_ushort v6, v[4:5], off offset:128
	global_load_ushort v7, v[4:5], off
	global_load_ushort v14, v[4:5], off offset:-256
	global_load_ushort v15, v[4:5], off offset:-128
	global_load_dword v20, v[0:1], off offset:256
	global_load_dword v21, v[0:1], off offset:512
	global_load_dword v22, v[0:1], off offset:768
	v_add_co_u32_e32 v192, vcc, 0x9000, v4
	v_addc_co_u32_e32 v193, vcc, 0, v5, vcc
	global_load_ushort v200, v[192:193], off offset:-256
	global_load_ushort v201, v[192:193], off offset:-128
	global_load_ushort v202, v[192:193], off
	global_load_ushort v203, v[192:193], off offset:128
	v_add_co_u32_e32 v194, vcc, 0x9000, v192
	v_addc_co_u32_e32 v195, vcc, 0, v193, vcc
	global_load_ushort v204, v[194:195], off offset:-256
	global_load_ushort v205, v[194:195], off offset:-128
	global_load_ushort v206, v[194:195], off
	global_load_ushort v207, v[194:195], off offset:128
	v_add_co_u32_e32 v196, vcc, 0x9000, v194
	v_addc_co_u32_e32 v197, vcc, 0, v195, vcc
	global_load_ushort v208, v[196:197], off offset:-256
	global_load_ushort v209, v[196:197], off offset:-128
	global_load_ushort v210, v[196:197], off
	global_load_ushort v211, v[196:197], off offset:128
	s_add_i32 s3, s22, s24
	s_mul_i32 s2, s3, 0x1200
	s_add_i32 s8, s3, 8
	s_mul_hi_u32 s9, s8, 0x1200
	s_add_i32 s8, s2, 0x9000
	s_add_u32 s8, s4, s8
	s_addc_u32 s9, s5, s9
	s_waitcnt vmcnt(18)
	v_lshlrev_b32_e32 v6, 16, v6
	s_waitcnt vmcnt(17)
	v_lshlrev_b32_e32 v7, 16, v7
	v_mul_f32_e32 v10, 0x3d372713, v7
	v_mul_f32_e32 v10, v10, v7
	v_mov_b32_e32 v11, v7
	v_fmac_f32_e32 v11, v10, v11
	v_mul_f32_e32 v10, 0x3f4c422a, v11
	v_add_f32_e32 v10, v10, v10
	v_mul_f32_e32 v10, 0x3fb8aa3b, v10
	s_waitcnt vmcnt(16)
	v_lshlrev_b32_e32 v14, 16, v14
	v_exp_f32_e32 v10, v10
	v_mul_f32_e32 v16, 0x3d372713, v14
	v_mul_f32_e32 v16, v16, v14
	v_mov_b32_e32 v17, v14
	s_waitcnt vmcnt(15)
	v_lshlrev_b32_e32 v15, 16, v15
	v_fmac_f32_e32 v17, v16, v17
	v_mul_f32_e32 v16, 0x3f4c422a, v17
	v_mul_f32_e32 v17, 0x3d372713, v15
	v_add_f32_e32 v10, 1.0, v10
	v_mul_f32_e32 v17, v17, v15
	v_mov_b32_e32 v18, v15
	v_rcp_f32_e32 v11, v10
	v_mul_f32_e32 v10, 0x3d372713, v6
	v_fmac_f32_e32 v18, v17, v18
	v_mul_f32_e32 v10, v10, v6
	v_mov_b32_e32 v12, v6
	v_mul_f32_e32 v17, 0x3f4c422a, v18
	v_fmac_f32_e32 v12, v10, v12
	v_add_f32_e32 v16, v16, v16
	v_add_f32_e32 v17, v17, v17
	v_mul_f32_e32 v10, 0x3f4c422a, v12
	v_mul_f32_e32 v16, 0x3fb8aa3b, v16
	v_mul_f32_e32 v17, 0x3fb8aa3b, v17
	v_add_f32_e32 v10, v10, v10
	v_exp_f32_e32 v16, v16
	v_exp_f32_e32 v17, v17
	v_mul_f32_e32 v10, 0x3fb8aa3b, v10
	v_exp_f32_e32 v10, v10
	v_add_f32_e32 v16, 1.0, v16
	v_add_f32_e32 v17, 1.0, v17
	v_rcp_f32_e32 v16, v16
	v_rcp_f32_e32 v17, v17
	v_add_f32_e32 v10, 1.0, v10
	v_rcp_f32_e32 v10, v10
	v_pk_mul_f32 v[14:15], v[14:15], 0.5 op_sel_hi:[1,0]
	v_pk_fma_f32 v[16:17], v[16:17], 2.0, 1.0 op_sel_hi:[1,0,0] neg_lo:[1,0,0] neg_hi:[1,0,0]
	v_pk_mul_f32 v[6:7], v[6:7], 0.5 op_sel_hi:[1,0]
	v_pk_add_f32 v[16:17], v[16:17], 1.0 op_sel_hi:[1,0]
	v_pk_fma_f32 v[10:11], v[10:11], 2.0, 1.0 op_sel_hi:[1,0,0] neg_lo:[1,0,0] neg_hi:[1,0,0]
	v_pk_mul_f32 v[18:19], v[14:15], v[16:17]
	v_pk_add_f32 v[10:11], v[10:11], 1.0 op_sel_hi:[1,0]
	v_add_f32_e32 v18, 0, v18
	v_pk_mul_f32 v[12:13], v[6:7], v[10:11]
	v_add_f32_e32 v18, v18, v19
	v_add_f32_e32 v13, v18, v13
	v_add_f32_e32 v12, v13, v12
	s_nop 1
	v_add_f32_dpp v12, v12, v12 quad_perm:[1,0,3,2] row_mask:0xf bank_mask:0xf
	s_nop 1
	v_add_f32_dpp v12, v12, v12 quad_perm:[2,3,0,1] row_mask:0xf bank_mask:0xf
	s_nop 1
	v_add_f32_dpp v12, v12, v12 row_half_mirror row_mask:0xf bank_mask:0xf
	s_nop 1
	v_add_f32_dpp v12, v12, v12 row_mirror row_mask:0xf bank_mask:0xf
	ds_bpermute_b32 v13, v53, v12
	s_waitcnt lgkmcnt(0)
	v_add_f32_e32 v12, v12, v13
	ds_bpermute_b32 v13, v54, v12
	s_waitcnt lgkmcnt(0)
	v_add_f32_e32 v12, v12, v13
	v_mul_f32_e32 v12, 0x3b800000, v12
	v_pk_fma_f32 v[14:15], v[14:15], v[16:17], v[12:13] op_sel_hi:[1,1,0] neg_lo:[0,0,1] neg_hi:[0,0,1]
	v_pk_fma_f32 v[6:7], v[6:7], v[10:11], v[12:13] op_sel_hi:[1,1,0] neg_lo:[0,0,1] neg_hi:[0,0,1]
	v_pk_mul_f32 v[16:17], v[14:15], v[14:15]
	v_pk_mul_f32 v[10:11], v[6:7], v[6:7]
	v_add_f32_e32 v12, v16, v17
	v_add_f32_e32 v11, v11, v12
	v_add_f32_e32 v10, v10, v11
	s_nop 1
	v_add_f32_dpp v10, v10, v10 quad_perm:[1,0,3,2] row_mask:0xf bank_mask:0xf
	s_nop 1
	v_add_f32_dpp v10, v10, v10 quad_perm:[2,3,0,1] row_mask:0xf bank_mask:0xf
	s_nop 1
	v_add_f32_dpp v10, v10, v10 row_half_mirror row_mask:0xf bank_mask:0xf
	s_nop 1
	v_add_f32_dpp v10, v10, v10 row_mirror row_mask:0xf bank_mask:0xf
	ds_bpermute_b32 v11, v53, v10
	s_waitcnt lgkmcnt(0)
	v_add_f32_e32 v10, v10, v11
	ds_bpermute_b32 v11, v54, v10
	s_waitcnt lgkmcnt(0)
	v_add_f32_e32 v10, v10, v11
	v_fmamk_f32 v10, v10, 0x3b800000, v176
	v_cmp_gt_f32_e32 vcc, s75, v10
	v_mul_f32_e32 v11, 0x4b800000, v10
	s_nop 0
	v_cndmask_b32_e32 v10, v10, v11, vcc
	v_rsq_f32_e32 v10, v10
	s_nop 0
	v_mul_f32_e32 v11, 0x45800000, v10
	v_cndmask_b32_e32 v10, v10, v11, vcc
	v_mul_f32_e32 v11, v14, v10
	v_mul_f32_e32 v11, v8, v11
	v_cvt_pk_bf16_f32 v11, v11, v2
	v_mul_f32_e32 v7, v7, v10
	v_mul_f32_e32 v6, v6, v10
	ds_write_b16 v9, v11
	v_mul_f32_e32 v11, v15, v10
	s_waitcnt vmcnt(13)
	v_mul_f32_e32 v7, v21, v7
	s_waitcnt vmcnt(12)
	v_mul_f32_e32 v6, v22, v6
	v_mul_f32_e32 v11, v20, v11
	v_cvt_pk_bf16_f32 v7, v7, v2
	v_cvt_pk_bf16_f32 v6, v6, v2
	v_cvt_pk_bf16_f32 v11, v11, v2
	ds_write_b16 v9, v7 offset:33792
	ds_write_b16 v9, v6 offset:50688
	v_lshl_add_u64 v[6:7], s[8:9], 0, v[40:41]
	ds_write_b16 v9, v11 offset:16896
	v_lshl_add_u64 v[10:11], v[6:7], 0, s[96:97]
	s_waitcnt vmcnt(8)
	v_mov_b32_e32 v12, v203
	v_mov_b32_e32 v13, v202
	v_add_co_u32_e32 v6, vcc, s74, v6
	s_add_i32 s8, s3, 16
	s_nop 0
	v_addc_co_u32_e32 v7, vcc, 0, v7, vcc
	v_mov_b32_e32 v6, v200
	s_nop 0
	v_mov_b32_e32 v7, v201
	s_mul_hi_u32 s9, s8, 0x1200
	s_add_i32 s8, s2, 0x12000
	s_add_u32 s8, s4, s8
	s_addc_u32 s9, s5, s9
	s_add_i32 s3, s3, 24
	s_add_i32 s2, s2, 0x1b000
	s_mul_hi_u32 s3, s3, 0x1200
	s_add_u32 s2, s4, s2
	s_addc_u32 s3, s5, s3
	s_add_i32 s24, s24, 32
	s_cmpk_eq_i32 s24, 0x80
	v_lshlrev_b32_e32 v12, 16, v12
	v_lshlrev_b32_e32 v13, 16, v13
	v_mul_f32_e32 v14, 0x3d372713, v13
	v_mul_f32_e32 v14, v14, v13
	v_mov_b32_e32 v15, v13
	v_fmac_f32_e32 v15, v14, v15
	v_mul_f32_e32 v14, 0x3f4c422a, v15
	v_add_f32_e32 v14, v14, v14
	v_mul_f32_e32 v14, 0x3fb8aa3b, v14
	v_lshlrev_b32_e32 v6, 16, v6
	v_exp_f32_e32 v14, v14
	v_mul_f32_e32 v10, 0x3d372713, v6
	v_mul_f32_e32 v10, v10, v6
	v_mov_b32_e32 v11, v6
	v_lshlrev_b32_e32 v7, 16, v7
	v_fmac_f32_e32 v11, v10, v11
	v_mul_f32_e32 v10, 0x3f4c422a, v11
	v_mul_f32_e32 v11, 0x3d372713, v7
	v_add_f32_e32 v14, 1.0, v14
	v_mul_f32_e32 v11, v11, v7
	v_mov_b32_e32 v18, v7
	v_rcp_f32_e32 v15, v14
	v_mul_f32_e32 v14, 0x3d372713, v12
	v_fmac_f32_e32 v18, v11, v18
	v_mul_f32_e32 v14, v14, v12
	v_mov_b32_e32 v16, v12
	v_mul_f32_e32 v11, 0x3f4c422a, v18
	v_fmac_f32_e32 v16, v14, v16
	v_add_f32_e32 v10, v10, v10
	v_add_f32_e32 v11, v11, v11
	v_mul_f32_e32 v14, 0x3f4c422a, v16
	v_mul_f32_e32 v10, 0x3fb8aa3b, v10
	v_mul_f32_e32 v11, 0x3fb8aa3b, v11
	v_add_f32_e32 v14, v14, v14
	v_exp_f32_e32 v10, v10
	v_exp_f32_e32 v11, v11
	v_mul_f32_e32 v14, 0x3fb8aa3b, v14
	v_exp_f32_e32 v14, v14
	v_add_f32_e32 v10, 1.0, v10
	v_add_f32_e32 v11, 1.0, v11
	v_rcp_f32_e32 v10, v10
	v_rcp_f32_e32 v11, v11
	v_add_f32_e32 v14, 1.0, v14
	v_rcp_f32_e32 v14, v14
	v_pk_mul_f32 v[6:7], v[6:7], 0.5 op_sel_hi:[1,0]
	v_pk_fma_f32 v[10:11], v[10:11], 2.0, 1.0 op_sel_hi:[1,0,0] neg_lo:[1,0,0] neg_hi:[1,0,0]
	v_pk_mul_f32 v[12:13], v[12:13], 0.5 op_sel_hi:[1,0]
	v_pk_add_f32 v[10:11], v[10:11], 1.0 op_sel_hi:[1,0]
	v_pk_fma_f32 v[14:15], v[14:15], 2.0, 1.0 op_sel_hi:[1,0,0] neg_lo:[1,0,0] neg_hi:[1,0,0]
	v_pk_mul_f32 v[18:19], v[6:7], v[10:11]
	v_pk_add_f32 v[14:15], v[14:15], 1.0 op_sel_hi:[1,0]
	v_add_f32_e32 v18, 0, v18
	v_pk_mul_f32 v[16:17], v[12:13], v[14:15]
	v_add_f32_e32 v18, v18, v19
	v_add_f32_e32 v17, v18, v17
	v_add_f32_e32 v16, v17, v16
	s_nop 1
	v_add_f32_dpp v16, v16, v16 quad_perm:[1,0,3,2] row_mask:0xf bank_mask:0xf
	s_nop 1
	v_add_f32_dpp v16, v16, v16 quad_perm:[2,3,0,1] row_mask:0xf bank_mask:0xf
	s_nop 1
	v_add_f32_dpp v16, v16, v16 row_half_mirror row_mask:0xf bank_mask:0xf
	s_nop 1
	v_add_f32_dpp v16, v16, v16 row_mirror row_mask:0xf bank_mask:0xf
	ds_bpermute_b32 v17, v53, v16
	s_waitcnt lgkmcnt(0)
	v_add_f32_e32 v16, v16, v17
	ds_bpermute_b32 v17, v54, v16
	s_waitcnt lgkmcnt(0)
	v_add_f32_e32 v16, v16, v17
	v_mul_f32_e32 v16, 0x3b800000, v16
	v_pk_fma_f32 v[6:7], v[6:7], v[10:11], v[16:17] op_sel_hi:[1,1,0] neg_lo:[0,0,1] neg_hi:[0,0,1]
	v_pk_fma_f32 v[12:13], v[12:13], v[14:15], v[16:17] op_sel_hi:[1,1,0] neg_lo:[0,0,1] neg_hi:[0,0,1]
	v_pk_mul_f32 v[10:11], v[6:7], v[6:7]
	v_pk_mul_f32 v[14:15], v[12:13], v[12:13]
	v_add_f32_e32 v10, v10, v11
	v_add_f32_e32 v10, v15, v10
	v_add_f32_e32 v10, v14, v10
	s_nop 1
	v_add_f32_dpp v10, v10, v10 quad_perm:[1,0,3,2] row_mask:0xf bank_mask:0xf
	s_nop 1
	v_add_f32_dpp v10, v10, v10 quad_perm:[2,3,0,1] row_mask:0xf bank_mask:0xf
	s_nop 1
	v_add_f32_dpp v10, v10, v10 row_half_mirror row_mask:0xf bank_mask:0xf
	s_nop 1
	v_add_f32_dpp v10, v10, v10 row_mirror row_mask:0xf bank_mask:0xf
	ds_bpermute_b32 v11, v53, v10
	s_waitcnt lgkmcnt(0)
	v_add_f32_e32 v10, v10, v11
	ds_bpermute_b32 v11, v54, v10
	s_waitcnt lgkmcnt(0)
	v_add_f32_e32 v10, v10, v11
	v_fmamk_f32 v10, v10, 0x3b800000, v176
	v_cmp_gt_f32_e32 vcc, s75, v10
	v_mul_f32_e32 v11, 0x4b800000, v10
	s_nop 0
	v_cndmask_b32_e32 v10, v10, v11, vcc
	v_rsq_f32_e32 v10, v10
	s_nop 0
	v_mul_f32_e32 v11, 0x45800000, v10
	v_cndmask_b32_e32 v10, v10, v11, vcc
	v_mul_f32_e32 v6, v6, v10
	v_mul_f32_e32 v6, v8, v6
	v_cvt_pk_bf16_f32 v6, v6, v2
	ds_write_b16 v9, v6 offset:16
	v_mul_f32_e32 v6, v7, v10
	v_mul_f32_e32 v6, v20, v6
	v_cvt_pk_bf16_f32 v6, v6, v2
	ds_write_b16 v9, v6 offset:16912
	v_mul_f32_e32 v6, v13, v10
	v_mul_f32_e32 v6, v21, v6
	v_cvt_pk_bf16_f32 v6, v6, v2
	ds_write_b16 v9, v6 offset:33808
	v_mul_f32_e32 v6, v12, v10
	v_mul_f32_e32 v6, v22, v6
	v_cvt_pk_bf16_f32 v6, v6, v2
	ds_write_b16 v9, v6 offset:50704
	v_lshl_add_u64 v[6:7], s[8:9], 0, v[40:41]
	v_lshl_add_u64 v[10:11], v[6:7], 0, s[96:97]
	s_waitcnt vmcnt(4)
	v_mov_b32_e32 v12, v207
	v_mov_b32_e32 v13, v206
	v_add_co_u32_e32 v6, vcc, s74, v6
	v_lshlrev_b32_e32 v12, 16, v12
	v_addc_co_u32_e32 v7, vcc, 0, v7, vcc
	v_mov_b32_e32 v6, v204
	s_nop 0
	v_mov_b32_e32 v7, v205
	v_lshlrev_b32_e32 v13, 16, v13
	v_mul_f32_e32 v14, 0x3d372713, v13
	v_mul_f32_e32 v14, v14, v13
	v_mov_b32_e32 v15, v13
	v_fmac_f32_e32 v15, v14, v15
	v_mul_f32_e32 v14, 0x3f4c422a, v15
	v_add_f32_e32 v14, v14, v14
	v_mul_f32_e32 v14, 0x3fb8aa3b, v14
	v_exp_f32_e32 v14, v14
	v_mov_b32_e32 v16, v12
	v_add_f32_e32 v14, 1.0, v14
	v_rcp_f32_e32 v15, v14
	v_mul_f32_e32 v14, 0x3d372713, v12
	v_mul_f32_e32 v14, v14, v12
	v_fmac_f32_e32 v16, v14, v16
	v_mul_f32_e32 v14, 0x3f4c422a, v16
	v_add_f32_e32 v14, v14, v14
	v_mul_f32_e32 v14, 0x3fb8aa3b, v14
	v_exp_f32_e32 v14, v14
	v_pk_mul_f32 v[12:13], v[12:13], 0.5 op_sel_hi:[1,0]
	v_add_f32_e32 v14, 1.0, v14
	v_rcp_f32_e32 v14, v14
	v_lshlrev_b32_e32 v6, 16, v6
	v_mul_f32_e32 v10, 0x3d372713, v6
	v_mul_f32_e32 v10, v10, v6
	v_mov_b32_e32 v11, v6
	v_lshlrev_b32_e32 v7, 16, v7
	v_fmac_f32_e32 v11, v10, v11
	v_mul_f32_e32 v10, 0x3f4c422a, v11
	v_mul_f32_e32 v11, 0x3d372713, v7
	v_mul_f32_e32 v11, v11, v7
	v_mov_b32_e32 v18, v7
	v_fmac_f32_e32 v18, v11, v18
	v_mul_f32_e32 v11, 0x3f4c422a, v18
	v_add_f32_e32 v10, v10, v10
	v_add_f32_e32 v11, v11, v11
	v_mul_f32_e32 v10, 0x3fb8aa3b, v10
	v_mul_f32_e32 v11, 0x3fb8aa3b, v11
	v_exp_f32_e32 v10, v10
	v_exp_f32_e32 v11, v11
	v_pk_mul_f32 v[6:7], v[6:7], 0.5 op_sel_hi:[1,0]
	v_pk_fma_f32 v[14:15], v[14:15], 2.0, 1.0 op_sel_hi:[1,0,0] neg_lo:[1,0,0] neg_hi:[1,0,0]
	v_add_f32_e32 v10, 1.0, v10
	v_add_f32_e32 v11, 1.0, v11
	v_rcp_f32_e32 v10, v10
	v_rcp_f32_e32 v11, v11
	v_pk_add_f32 v[14:15], v[14:15], 1.0 op_sel_hi:[1,0]
	v_pk_fma_f32 v[10:11], v[10:11], 2.0, 1.0 op_sel_hi:[1,0,0] neg_lo:[1,0,0] neg_hi:[1,0,0]
	s_nop 0
	v_pk_add_f32 v[10:11], v[10:11], 1.0 op_sel_hi:[1,0]
	v_pk_mul_f32 v[16:17], v[12:13], v[14:15]
	v_pk_mul_f32 v[18:19], v[6:7], v[10:11]
	s_nop 0
	v_add_f32_e32 v18, 0, v18
	v_add_f32_e32 v18, v18, v19
	v_add_f32_e32 v17, v18, v17
	v_add_f32_e32 v16, v17, v16
	s_nop 1
	v_add_f32_dpp v16, v16, v16 quad_perm:[1,0,3,2] row_mask:0xf bank_mask:0xf
	s_nop 1
	v_add_f32_dpp v16, v16, v16 quad_perm:[2,3,0,1] row_mask:0xf bank_mask:0xf
	s_nop 1
	v_add_f32_dpp v16, v16, v16 row_half_mirror row_mask:0xf bank_mask:0xf
	s_nop 1
	v_add_f32_dpp v16, v16, v16 row_mirror row_mask:0xf bank_mask:0xf
	ds_bpermute_b32 v17, v53, v16
	s_waitcnt lgkmcnt(0)
	v_add_f32_e32 v16, v16, v17
	ds_bpermute_b32 v17, v54, v16
	s_waitcnt lgkmcnt(0)
	v_add_f32_e32 v16, v16, v17
	v_mul_f32_e32 v16, 0x3b800000, v16
	v_pk_fma_f32 v[6:7], v[6:7], v[10:11], v[16:17] op_sel_hi:[1,1,0] neg_lo:[0,0,1] neg_hi:[0,0,1]
	v_pk_fma_f32 v[12:13], v[12:13], v[14:15], v[16:17] op_sel_hi:[1,1,0] neg_lo:[0,0,1] neg_hi:[0,0,1]
	v_pk_mul_f32 v[10:11], v[6:7], v[6:7]
	v_pk_mul_f32 v[14:15], v[12:13], v[12:13]
	v_add_f32_e32 v10, v10, v11
	v_add_f32_e32 v10, v15, v10
	v_add_f32_e32 v10, v14, v10
	s_nop 1
	v_add_f32_dpp v10, v10, v10 quad_perm:[1,0,3,2] row_mask:0xf bank_mask:0xf
	s_nop 1
	v_add_f32_dpp v10, v10, v10 quad_perm:[2,3,0,1] row_mask:0xf bank_mask:0xf
	s_nop 1
	v_add_f32_dpp v10, v10, v10 row_half_mirror row_mask:0xf bank_mask:0xf
	s_nop 1
	v_add_f32_dpp v10, v10, v10 row_mirror row_mask:0xf bank_mask:0xf
	ds_bpermute_b32 v11, v53, v10
	s_waitcnt lgkmcnt(0)
	v_add_f32_e32 v10, v10, v11
	ds_bpermute_b32 v11, v54, v10
	s_waitcnt lgkmcnt(0)
	v_add_f32_e32 v10, v10, v11
	v_fmamk_f32 v10, v10, 0x3b800000, v176
	v_cmp_gt_f32_e32 vcc, s75, v10
	v_mul_f32_e32 v11, 0x4b800000, v10
	s_nop 0
	v_cndmask_b32_e32 v10, v10, v11, vcc
	v_rsq_f32_e32 v10, v10
	s_nop 0
	v_mul_f32_e32 v11, 0x45800000, v10
	v_cndmask_b32_e32 v10, v10, v11, vcc
	v_mul_f32_e32 v6, v6, v10
	v_mul_f32_e32 v6, v8, v6
	v_cvt_pk_bf16_f32 v6, v6, v2
	ds_write_b16 v9, v6 offset:32
	v_mul_f32_e32 v6, v7, v10
	v_mul_f32_e32 v6, v20, v6
	v_cvt_pk_bf16_f32 v6, v6, v2
	ds_write_b16 v9, v6 offset:16928
	v_mul_f32_e32 v6, v13, v10
	v_mul_f32_e32 v6, v21, v6
	v_cvt_pk_bf16_f32 v6, v6, v2
	ds_write_b16 v9, v6 offset:33824
	v_mul_f32_e32 v6, v12, v10
	v_mul_f32_e32 v6, v22, v6
	v_cvt_pk_bf16_f32 v6, v6, v2
	ds_write_b16 v9, v6 offset:50720
	v_lshl_add_u64 v[6:7], s[2:3], 0, v[40:41]
	v_lshl_add_u64 v[10:11], v[6:7], 0, s[96:97]
	s_waitcnt vmcnt(0)
	v_mov_b32_e32 v12, v211
	v_mov_b32_e32 v13, v210
	v_add_co_u32_e32 v6, vcc, s74, v6
	s_mov_b64 s[2:3], 0x24000
	s_nop 0
	v_addc_co_u32_e32 v7, vcc, 0, v7, vcc
	v_mov_b32_e32 v6, v208
	s_nop 0
	v_mov_b32_e32 v7, v209
	v_lshl_add_u64 v[4:5], v[4:5], 0, s[2:3]
	v_lshlrev_b32_e32 v12, 16, v12
	v_lshlrev_b32_e32 v13, 16, v13
	v_mul_f32_e32 v14, 0x3d372713, v13
	v_mul_f32_e32 v14, v14, v13
	v_mov_b32_e32 v15, v13
	v_fmac_f32_e32 v15, v14, v15
	v_mul_f32_e32 v14, 0x3f4c422a, v15
	v_add_f32_e32 v14, v14, v14
	v_mul_f32_e32 v14, 0x3fb8aa3b, v14
	v_lshlrev_b32_e32 v6, 16, v6
	v_exp_f32_e32 v14, v14
	v_mul_f32_e32 v10, 0x3d372713, v6
	v_mul_f32_e32 v10, v10, v6
	v_mov_b32_e32 v11, v6
	v_lshlrev_b32_e32 v7, 16, v7
	v_fmac_f32_e32 v11, v10, v11
	v_mul_f32_e32 v10, 0x3f4c422a, v11
	v_mul_f32_e32 v11, 0x3d372713, v7
	v_add_f32_e32 v14, 1.0, v14
	v_mul_f32_e32 v11, v11, v7
	v_mov_b32_e32 v18, v7
	v_rcp_f32_e32 v15, v14
	v_mul_f32_e32 v14, 0x3d372713, v12
	v_fmac_f32_e32 v18, v11, v18
	v_mul_f32_e32 v14, v14, v12
	v_mov_b32_e32 v16, v12
	v_mul_f32_e32 v11, 0x3f4c422a, v18
	v_fmac_f32_e32 v16, v14, v16
	v_add_f32_e32 v10, v10, v10
	v_add_f32_e32 v11, v11, v11
	v_mul_f32_e32 v14, 0x3f4c422a, v16
	v_mul_f32_e32 v10, 0x3fb8aa3b, v10
	v_mul_f32_e32 v11, 0x3fb8aa3b, v11
	v_add_f32_e32 v14, v14, v14
	v_exp_f32_e32 v10, v10
	v_exp_f32_e32 v11, v11
	v_mul_f32_e32 v14, 0x3fb8aa3b, v14
	v_exp_f32_e32 v14, v14
	v_add_f32_e32 v10, 1.0, v10
	v_add_f32_e32 v11, 1.0, v11
	v_rcp_f32_e32 v10, v10
	v_rcp_f32_e32 v11, v11
	v_add_f32_e32 v14, 1.0, v14
	v_rcp_f32_e32 v14, v14
	v_pk_mul_f32 v[6:7], v[6:7], 0.5 op_sel_hi:[1,0]
	v_pk_fma_f32 v[10:11], v[10:11], 2.0, 1.0 op_sel_hi:[1,0,0] neg_lo:[1,0,0] neg_hi:[1,0,0]
	v_pk_mul_f32 v[12:13], v[12:13], 0.5 op_sel_hi:[1,0]
	v_pk_add_f32 v[10:11], v[10:11], 1.0 op_sel_hi:[1,0]
	v_pk_fma_f32 v[14:15], v[14:15], 2.0, 1.0 op_sel_hi:[1,0,0] neg_lo:[1,0,0] neg_hi:[1,0,0]
	v_pk_mul_f32 v[18:19], v[6:7], v[10:11]
	v_pk_add_f32 v[14:15], v[14:15], 1.0 op_sel_hi:[1,0]
	v_add_f32_e32 v18, 0, v18
	v_pk_mul_f32 v[16:17], v[12:13], v[14:15]
	v_add_f32_e32 v18, v18, v19
	v_add_f32_e32 v17, v18, v17
	v_add_f32_e32 v16, v17, v16
	s_nop 1
	v_add_f32_dpp v16, v16, v16 quad_perm:[1,0,3,2] row_mask:0xf bank_mask:0xf
	s_nop 1
	v_add_f32_dpp v16, v16, v16 quad_perm:[2,3,0,1] row_mask:0xf bank_mask:0xf
	s_nop 1
	v_add_f32_dpp v16, v16, v16 row_half_mirror row_mask:0xf bank_mask:0xf
	s_nop 1
	v_add_f32_dpp v16, v16, v16 row_mirror row_mask:0xf bank_mask:0xf
	ds_bpermute_b32 v17, v53, v16
	s_waitcnt lgkmcnt(0)
	v_add_f32_e32 v16, v16, v17
	ds_bpermute_b32 v17, v54, v16
	s_waitcnt lgkmcnt(0)
	v_add_f32_e32 v16, v16, v17
	v_mul_f32_e32 v16, 0x3b800000, v16
	v_pk_fma_f32 v[6:7], v[6:7], v[10:11], v[16:17] op_sel_hi:[1,1,0] neg_lo:[0,0,1] neg_hi:[0,0,1]
	v_pk_fma_f32 v[12:13], v[12:13], v[14:15], v[16:17] op_sel_hi:[1,1,0] neg_lo:[0,0,1] neg_hi:[0,0,1]
	v_pk_mul_f32 v[10:11], v[6:7], v[6:7]
	v_pk_mul_f32 v[14:15], v[12:13], v[12:13]
	v_add_f32_e32 v10, v10, v11
	v_add_f32_e32 v10, v15, v10
	v_add_f32_e32 v10, v14, v10
	s_nop 1
	v_add_f32_dpp v10, v10, v10 quad_perm:[1,0,3,2] row_mask:0xf bank_mask:0xf
	s_nop 1
	v_add_f32_dpp v10, v10, v10 quad_perm:[2,3,0,1] row_mask:0xf bank_mask:0xf
	s_nop 1
	v_add_f32_dpp v10, v10, v10 row_half_mirror row_mask:0xf bank_mask:0xf
	s_nop 1
	v_add_f32_dpp v10, v10, v10 row_mirror row_mask:0xf bank_mask:0xf
	ds_bpermute_b32 v11, v53, v10
	s_waitcnt lgkmcnt(0)
	v_add_f32_e32 v10, v10, v11
	ds_bpermute_b32 v11, v54, v10
	s_waitcnt lgkmcnt(0)
	v_add_f32_e32 v10, v10, v11
	v_fmamk_f32 v10, v10, 0x3b800000, v176
	v_cmp_gt_f32_e32 vcc, s75, v10
	v_mul_f32_e32 v11, 0x4b800000, v10
	s_nop 0
	v_cndmask_b32_e32 v10, v10, v11, vcc
	v_rsq_f32_e32 v10, v10
	s_nop 0
	v_mul_f32_e32 v11, 0x45800000, v10
	v_cndmask_b32_e32 v10, v10, v11, vcc
	v_mul_f32_e32 v6, v6, v10
	v_mul_f32_e32 v6, v8, v6
	v_cvt_pk_bf16_f32 v6, v6, v2
	ds_write_b16 v9, v6 offset:48
	v_mul_f32_e32 v6, v7, v10
	v_mul_f32_e32 v6, v20, v6
	v_cvt_pk_bf16_f32 v6, v6, v2
	ds_write_b16 v9, v6 offset:16944
	v_mul_f32_e32 v6, v13, v10
	v_mul_f32_e32 v6, v21, v6
	v_cvt_pk_bf16_f32 v6, v6, v2
	ds_write_b16 v9, v6 offset:33840
	v_mul_f32_e32 v6, v12, v10
	v_mul_f32_e32 v6, v22, v6
	v_cvt_pk_bf16_f32 v6, v6, v2
	ds_write_b16 v9, v6 offset:50736
	v_add_u32_e32 v9, 64, v9
	s_cbranch_scc0 .LBB0_287
	v_mov_b32_e32 v37, v2
	v_lshlrev_b64 v[4:5], 11, v[36:37]
	v_mad_u64_u32 v[44:45], s[2:3], v36, s61, v[38:39]
	v_lshl_add_u64 v[42:43], v[34:35], 0, v[4:5]
	s_mov_b64 s[2:3], 0
	v_mov_b32_e32 v37, v56
	v_mov_b64_e32 v[46:47], v[32:33]
	v_mov_b64_e32 v[48:49], v[30:31]
	s_waitcnt lgkmcnt(0)
	s_barrier
	s_branch .LBB0_290
